# v20 + GEMM loops: first k-step's MFMAs take srcC = 0 (no 64 v_mov accumulator zeroing per tile)
# speedup vs baseline: 1.0047x; 1.0047x over previous
.LBB0_228:
	s_cmpk_lt_i32 s33, 0x1040
	s_mov_b64 s[0:1], -1
	s_cbranch_scc0 .LBB0_345
	s_and_b32 s76, s33, 63
	s_lshl_b32 s10, s76, 19
	s_ashr_i32 s16, s33, 6
	s_lshl_b32 s0, s16, 19
	s_add_u32 s68, s88, 0x3f80000
	s_addc_u32 s69, s89, 0
	s_add_u32 s68, s68, s10
	s_addc_u32 s69, s69, 0
	s_add_u32 s70, s88, s0
	s_addc_u32 s71, s89, 0
	v_readfirstlane_b32 s65, v168
	v_lshrrev_b32_e32 v206, 3, v168
	v_bfe_u32 v207, v168, 4, 3
	v_and_b32_e32 v208, 7, v168
	v_xor_b32_e32 v207, v207, v208
	v_lshlrev_b32_e32 v207, 4, v207
	s_lshr_b32 s65, s65, 6
	s_lshl_b32 s65, s65, 10
	s_movk_i32 s64, 0x1000
	v_mul_lo_u32 v206, v206, s64
	v_add_u32_e32 v206, v206, v207
	v_add_u32_e32 v207, 0x20000, v206
	v_add_u32_e32 v208, 0x40000, v206
	v_add_u32_e32 v209, 0x60000, v206
	v_add_u32_e32 v210, v156, v158
	v_add_u32_e32 v214, v157, v158
	v_add_u32_e32 v211, v156, v159
	v_add_u32_e32 v215, v157, v159
	v_add_u32_e32 v212, v156, v160
	v_add_u32_e32 v216, v157, v160
	v_add_u32_e32 v213, v156, v161
	v_add_u32_e32 v217, v157, v161
	s_add_u32 m0, s65, 0x0
	s_nop 0
	global_load_lds_dwordx4 v206, s[68:69]
	s_add_u32 m0, s65, 0x1000
	s_nop 0
	global_load_lds_dwordx4 v207, s[68:69]
	s_add_u32 m0, s65, 0x2000
	s_nop 0
	global_load_lds_dwordx4 v208, s[68:69]
	s_add_u32 m0, s65, 0x3000
	s_nop 0
	global_load_lds_dwordx4 v209, s[68:69]
	s_add_u32 m0, s65, 0x8000
	s_nop 0
	global_load_lds_dwordx4 v206, s[70:71]
	s_add_u32 m0, s65, 0x9000
	s_nop 0
	global_load_lds_dwordx4 v207, s[70:71]
	s_add_u32 m0, s65, 0xa000
	s_nop 0
	global_load_lds_dwordx4 v208, s[70:71]
	s_add_u32 m0, s65, 0xb000
	s_nop 0
	global_load_lds_dwordx4 v209, s[70:71]
	s_add_u32 s68, s68, 0x80
	s_addc_u32 s69, s69, 0
	s_add_u32 s70, s70, 0x80
	s_addc_u32 s71, s71, 0
	s_add_u32 m0, s65, 0x4000
	s_nop 0
	global_load_lds_dwordx4 v206, s[68:69]
	s_add_u32 m0, s65, 0x5000
	s_nop 0
	global_load_lds_dwordx4 v207, s[68:69]
	s_add_u32 m0, s65, 0x6000
	s_nop 0
	global_load_lds_dwordx4 v208, s[68:69]
	s_add_u32 m0, s65, 0x7000
	s_nop 0
	global_load_lds_dwordx4 v209, s[68:69]
	s_add_u32 m0, s65, 0xc000
	s_nop 0
	global_load_lds_dwordx4 v206, s[70:71]
	s_add_u32 m0, s65, 0xd000
	s_nop 0
	global_load_lds_dwordx4 v207, s[70:71]
	s_add_u32 m0, s65, 0xe000
	s_nop 0
	global_load_lds_dwordx4 v208, s[70:71]
	s_add_u32 m0, s65, 0xf000
	s_nop 0
	global_load_lds_dwordx4 v209, s[70:71]
	s_add_u32 s68, s68, 0x80
	s_addc_u32 s69, s69, 0
	s_add_u32 s70, s70, 0x80
	s_addc_u32 s71, s71, 0
	s_waitcnt vmcnt(8)
	s_barrier
	ds_read_b128 v[64:67], v210 offset:0
	ds_read_b128 v[68:71], v210 offset:4096
	ds_read_b128 v[72:75], v214 offset:32768
	ds_read_b128 v[76:79], v214 offset:36864
	ds_read_b128 v[80:83], v211 offset:0
	ds_read_b128 v[84:87], v211 offset:4096
	ds_read_b128 v[88:91], v215 offset:32768
	ds_read_b128 v[92:95], v215 offset:36864
	ds_read_b128 v[96:99], v212 offset:0
	ds_read_b128 v[100:103], v212 offset:4096
	ds_read_b128 v[104:107], v216 offset:32768
	ds_read_b128 v[108:111], v216 offset:36864
	s_mov_b32 s64, 0
	ds_read_b128 v[112:115], v213 offset:0
	ds_read_b128 v[116:119], v213 offset:4096
	ds_read_b128 v[120:123], v217 offset:32768
	ds_read_b128 v[124:127], v217 offset:36864
	s_waitcnt lgkmcnt(12)
	v_mfma_f32_32x32x16_bf16 v[48:63], v[64:67], v[72:75], 0
	v_mfma_f32_32x32x16_bf16 v[32:47], v[64:67], v[76:79], 0
	v_mfma_f32_32x32x16_bf16 v[16:31], v[68:71], v[72:75], 0
	v_mfma_f32_32x32x16_bf16 v[0:15], v[68:71], v[76:79], 0
	s_waitcnt vmcnt(0) lgkmcnt(0)
	s_barrier
	s_branch .Lgm_body0_B

.Lgm_body0_B:
	ds_read_b128 v[64:67], v210 offset:16384
	s_add_u32 m0, s65, 0x0
	s_nop 0
	global_load_lds_dwordx4 v206, s[68:69]
	v_mfma_f32_32x32x16_bf16 v[48:63], v[80:83], v[88:91], v[48:63]
	ds_read_b128 v[68:71], v210 offset:20480
	s_add_u32 m0, s65, 0x1000
	s_nop 0
	global_load_lds_dwordx4 v207, s[68:69]
	v_mfma_f32_32x32x16_bf16 v[32:47], v[80:83], v[92:95], v[32:47]
	ds_read_b128 v[72:75], v214 offset:49152
	s_add_u32 m0, s65, 0x2000
	s_nop 0
	global_load_lds_dwordx4 v208, s[68:69]
	v_mfma_f32_32x32x16_bf16 v[16:31], v[84:87], v[88:91], v[16:31]
	ds_read_b128 v[76:79], v214 offset:53248
	s_add_u32 m0, s65, 0x3000
	s_nop 0
	global_load_lds_dwordx4 v209, s[68:69]
	v_mfma_f32_32x32x16_bf16 v[0:15], v[84:87], v[92:95], v[0:15]
	ds_read_b128 v[80:83], v211 offset:16384
	s_add_u32 m0, s65, 0x8000
	s_nop 0
	global_load_lds_dwordx4 v206, s[70:71]
	v_mfma_f32_32x32x16_bf16 v[48:63], v[96:99], v[104:107], v[48:63]
	ds_read_b128 v[84:87], v211 offset:20480
	s_add_u32 m0, s65, 0x9000
	s_nop 0
	global_load_lds_dwordx4 v207, s[70:71]
	v_mfma_f32_32x32x16_bf16 v[32:47], v[96:99], v[108:111], v[32:47]
	ds_read_b128 v[88:91], v215 offset:49152
	s_add_u32 m0, s65, 0xa000
	s_nop 0
	global_load_lds_dwordx4 v208, s[70:71]
	v_mfma_f32_32x32x16_bf16 v[16:31], v[100:103], v[104:107], v[16:31]
	ds_read_b128 v[92:95], v215 offset:53248
	s_add_u32 m0, s65, 0xb000
	s_nop 0
	global_load_lds_dwordx4 v209, s[70:71]
	v_mfma_f32_32x32x16_bf16 v[0:15], v[100:103], v[108:111], v[0:15]
	ds_read_b128 v[96:99], v212 offset:16384
	s_add_u32 s68, s68, 0x80
	s_addc_u32 s69, s69, 0
	s_add_u32 s70, s70, 0x80
	s_addc_u32 s71, s71, 0
	v_mfma_f32_32x32x16_bf16 v[48:63], v[112:115], v[120:123], v[48:63]
	ds_read_b128 v[100:103], v212 offset:20480
	v_mfma_f32_32x32x16_bf16 v[32:47], v[112:115], v[124:127], v[32:47]
	ds_read_b128 v[104:107], v216 offset:49152
	v_mfma_f32_32x32x16_bf16 v[16:31], v[116:119], v[120:123], v[16:31]
	ds_read_b128 v[108:111], v216 offset:53248
	v_mfma_f32_32x32x16_bf16 v[0:15], v[116:119], v[124:127], v[0:15]
	s_branch .Lgm_join0_B

.LBB0_864:
	s_and_b32 s6, s2, 0x1f80
	s_ashr_i32 s0, s45, 6
	s_lshl_b32 s40, s6, 11
	s_add_u32 s56, s88, s40
	s_addc_u32 s57, s89, 0
	s_ashr_i32 s1, s0, 31
	s_lshl_b64 s[0:1], s[0:1], 18
	s_add_u32 s58, s88, s0
	s_addc_u32 s59, s89, s1
	s_add_u32 s58, s58, 0x2280000
	s_addc_u32 s59, s59, 0
	s_mov_b64 s[0:1], vcc
	s_mov_b64 s[4:5], vcc
	s_mov_b64 s[0:1], vcc
	s_mov_b64 s[4:5], vcc
	s_mov_b64 s[0:1], vcc
	s_and_b32 s0, s45, 0xffffffc0
	s_ashr_i32 s1, s0, 31
	s_or_b32 s4, s6, 32
	s_add_i32 s45, s45, s92
	s_add_i32 s2, s2, s33
	s_cmpk_lt_i32 s45, 0x400
	v_readfirstlane_b32 s61, v168
	v_lshrrev_b32_e32 v64, 3, v168
	v_bfe_u32 v65, v168, 4, 3
	v_and_b32_e32 v66, 7, v168
	v_xor_b32_e32 v65, v65, v66
	v_lshlrev_b32_e32 v65, 4, v65
	s_lshr_b32 s61, s61, 6
	s_lshl_b32 s61, s61, 10
	s_movk_i32 s60, 0x800
	v_mul_lo_u32 v64, v64, s60
	v_add_u32_e32 v64, v64, v65
	v_add_u32_e32 v65, 0x10000, v64
	v_add_u32_e32 v66, 0x20000, v64
	v_add_u32_e32 v67, 0x30000, v64
	s_add_u32 m0, s61, 0x0
	s_nop 0
	global_load_lds_dwordx4 v64, s[56:57]
	s_add_u32 m0, s61, 0x1000
	s_nop 0
	global_load_lds_dwordx4 v65, s[56:57]
	s_add_u32 m0, s61, 0x2000
	s_nop 0
	global_load_lds_dwordx4 v66, s[56:57]
	s_add_u32 m0, s61, 0x3000
	s_nop 0
	global_load_lds_dwordx4 v67, s[56:57]
	s_add_u32 m0, s61, 0x8000
	s_nop 0
	global_load_lds_dwordx4 v64, s[58:59]
	s_add_u32 m0, s61, 0x9000
	s_nop 0
	global_load_lds_dwordx4 v65, s[58:59]
	s_add_u32 m0, s61, 0xa000
	s_nop 0
	global_load_lds_dwordx4 v66, s[58:59]
	s_add_u32 m0, s61, 0xb000
	s_nop 0
	global_load_lds_dwordx4 v67, s[58:59]
	s_add_u32 s56, s56, 0x80
	s_addc_u32 s57, s57, 0
	s_add_u32 s58, s58, 0x80
	s_addc_u32 s59, s59, 0
	s_add_u32 m0, s61, 0x4000
	s_nop 0
	global_load_lds_dwordx4 v64, s[56:57]
	s_add_u32 m0, s61, 0x5000
	s_nop 0
	global_load_lds_dwordx4 v65, s[56:57]
	s_add_u32 m0, s61, 0x6000
	s_nop 0
	global_load_lds_dwordx4 v66, s[56:57]
	s_add_u32 m0, s61, 0x7000
	s_nop 0
	global_load_lds_dwordx4 v67, s[56:57]
	s_add_u32 m0, s61, 0xc000
	s_nop 0
	global_load_lds_dwordx4 v64, s[58:59]
	s_add_u32 m0, s61, 0xd000
	s_nop 0
	global_load_lds_dwordx4 v65, s[58:59]
	s_add_u32 m0, s61, 0xe000
	s_nop 0
	global_load_lds_dwordx4 v66, s[58:59]
	s_add_u32 m0, s61, 0xf000
	s_nop 0
	global_load_lds_dwordx4 v67, s[58:59]
	s_add_u32 s56, s56, 0x80
	s_addc_u32 s57, s57, 0
	s_add_u32 s58, s58, 0x80
	s_addc_u32 s59, s59, 0
	s_waitcnt vmcnt(8)
	s_barrier
	ds_read_b128 v[186:189], v111 offset:0
	ds_read_b128 v[190:193], v111 offset:4096
	ds_read_b128 v[194:197], v112 offset:32768
	ds_read_b128 v[198:201], v112 offset:36864
	ds_read_b128 v[202:205], v113 offset:0
	ds_read_b128 v[206:209], v113 offset:4096
	ds_read_b128 v[210:213], v114 offset:32768
	ds_read_b128 v[214:217], v114 offset:36864
	ds_read_b128 v[218:221], v115 offset:0
	ds_read_b128 v[222:225], v115 offset:4096
	ds_read_b128 v[226:229], v116 offset:32768
	ds_read_b128 v[230:233], v116 offset:36864
	s_mov_b32 s60, 0
	ds_read_b128 v[234:237], v117 offset:0
	ds_read_b128 v[238:241], v117 offset:4096
	ds_read_b128 v[242:245], v118 offset:32768
	ds_read_b128 v[246:249], v118 offset:36864
	s_waitcnt lgkmcnt(12)
	v_mfma_f32_32x32x16_bf16 v[32:47], v[186:189], v[194:197], 0
	v_mfma_f32_32x32x16_bf16 v[48:63], v[186:189], v[198:201], 0
	v_mfma_f32_32x32x16_bf16 v[0:15], v[190:193], v[194:197], 0
	v_mfma_f32_32x32x16_bf16 v[16:31], v[190:193], v[198:201], 0
	s_waitcnt vmcnt(0) lgkmcnt(0)
	s_barrier
	s_branch .Lgm_body0_E

.Lgm_body0_E:
	ds_read_b128 v[186:189], v111 offset:16384
	s_add_u32 m0, s61, 0x0
	s_nop 0
	global_load_lds_dwordx4 v64, s[56:57]
	v_mfma_f32_32x32x16_bf16 v[32:47], v[202:205], v[210:213], v[32:47]
	ds_read_b128 v[190:193], v111 offset:20480
	s_add_u32 m0, s61, 0x1000
	s_nop 0
	global_load_lds_dwordx4 v65, s[56:57]
	v_mfma_f32_32x32x16_bf16 v[48:63], v[202:205], v[214:217], v[48:63]
	ds_read_b128 v[194:197], v112 offset:49152
	s_add_u32 m0, s61, 0x2000
	s_nop 0
	global_load_lds_dwordx4 v66, s[56:57]
	v_mfma_f32_32x32x16_bf16 v[0:15], v[206:209], v[210:213], v[0:15]
	ds_read_b128 v[198:201], v112 offset:53248
	s_add_u32 m0, s61, 0x3000
	s_nop 0
	global_load_lds_dwordx4 v67, s[56:57]
	v_mfma_f32_32x32x16_bf16 v[16:31], v[206:209], v[214:217], v[16:31]
	ds_read_b128 v[202:205], v113 offset:16384
	s_add_u32 m0, s61, 0x8000
	s_nop 0
	global_load_lds_dwordx4 v64, s[58:59]
	v_mfma_f32_32x32x16_bf16 v[32:47], v[218:221], v[226:229], v[32:47]
	ds_read_b128 v[206:209], v113 offset:20480
	s_add_u32 m0, s61, 0x9000
	s_nop 0
	global_load_lds_dwordx4 v65, s[58:59]
	v_mfma_f32_32x32x16_bf16 v[48:63], v[218:221], v[230:233], v[48:63]
	ds_read_b128 v[210:213], v114 offset:49152
	s_add_u32 m0, s61, 0xa000
	s_nop 0
	global_load_lds_dwordx4 v66, s[58:59]
	v_mfma_f32_32x32x16_bf16 v[0:15], v[222:225], v[226:229], v[0:15]
	ds_read_b128 v[214:217], v114 offset:53248
	s_add_u32 m0, s61, 0xb000
	s_nop 0
	global_load_lds_dwordx4 v67, s[58:59]
	v_mfma_f32_32x32x16_bf16 v[16:31], v[222:225], v[230:233], v[16:31]
	ds_read_b128 v[218:221], v115 offset:16384
	s_add_u32 s56, s56, 0x80
	s_addc_u32 s57, s57, 0
	s_add_u32 s58, s58, 0x80
	s_addc_u32 s59, s59, 0
	v_mfma_f32_32x32x16_bf16 v[32:47], v[234:237], v[242:245], v[32:47]
	ds_read_b128 v[222:225], v115 offset:20480
	v_mfma_f32_32x32x16_bf16 v[48:63], v[234:237], v[246:249], v[48:63]
	ds_read_b128 v[226:229], v116 offset:49152
	v_mfma_f32_32x32x16_bf16 v[0:15], v[238:241], v[242:245], v[0:15]
	ds_read_b128 v[230:233], v116 offset:53248
	v_mfma_f32_32x32x16_bf16 v[16:31], v[238:241], v[246:249], v[16:31]
	s_branch .Lgm_join0_E

.LBB0_923:
	s_lshr_b32 s0, s2, 1
	s_mul_i32 s0, s0, s92
	s_add_i32 s0, s0, s94
	s_lshl_b32 s1, s0, 7
	s_lshl_b32 s0, s0, 1
	s_and_b32 s9, s2, 1
	s_and_b32 s20, s1, 0x1f80
	s_and_b32 s8, s0, 0xffffff80
	s_bitcmp1_b32 s2, 0
	s_cselect_b64 s[6:7], -1, 0
	s_cmp_eq_u32 s9, 0
	s_cselect_b64 s[0:1], -1, 0
	s_and_b64 s[22:23], s[0:1], exec
	s_cselect_b32 s9, s11, 0x1000000
	s_cselect_b32 s24, s12, 0x2a80000
	s_cselect_b32 s21, s13, 0xbf80000
	s_add_u32 s9, s88, s9
	s_addc_u32 s23, s89, 0
	s_lshl_b32 s22, s20, 11
	s_add_u32 s22, s9, s22
	s_addc_u32 s23, s23, 0
	s_mov_b64 s[56:57], s[22:23]
	s_add_u32 s26, s88, s24
	s_addc_u32 s27, s89, 0
	s_ashr_i32 s9, s8, 31
	s_lshl_b64 s[24:25], s[8:9], 11
	s_add_u32 s24, s26, s24
	s_addc_u32 s25, s27, s25
	s_mov_b64 s[58:59], s[24:25]
	s_add_u32 s21, s88, s21
	s_addc_u32 s23, s89, 0
	s_lshl_b64 s[8:9], s[8:9], 1
	s_add_u32 s22, s21, s8
	s_addc_u32 s23, s23, s9
	v_lshl_add_u64 v[136:137], v[94:95], 0, s[8:9]
	s_mov_b64 s[8:9], -1
	s_and_b64 vcc, s[0:1], exec
	v_readfirstlane_b32 s61, v168
	v_lshrrev_b32_e32 v64, 3, v168
	v_bfe_u32 v65, v168, 4, 3
	v_and_b32_e32 v66, 7, v168
	v_xor_b32_e32 v65, v65, v66
	v_lshlrev_b32_e32 v65, 4, v65
	s_lshr_b32 s61, s61, 6
	s_lshl_b32 s61, s61, 10
	s_movk_i32 s60, 0x800
	v_mul_lo_u32 v64, v64, s60
	v_add_u32_e32 v64, v64, v65
	v_add_u32_e32 v65, 0x10000, v64
	v_add_u32_e32 v66, 0x20000, v64
	v_add_u32_e32 v67, 0x30000, v64
	s_add_u32 m0, s61, 0x0
	s_nop 0
	global_load_lds_dwordx4 v64, s[56:57]
	s_add_u32 m0, s61, 0x1000
	s_nop 0
	global_load_lds_dwordx4 v65, s[56:57]
	s_add_u32 m0, s61, 0x2000
	s_nop 0
	global_load_lds_dwordx4 v66, s[56:57]
	s_add_u32 m0, s61, 0x3000
	s_nop 0
	global_load_lds_dwordx4 v67, s[56:57]
	s_add_u32 m0, s61, 0x8000
	s_nop 0
	global_load_lds_dwordx4 v64, s[58:59]
	s_add_u32 m0, s61, 0x9000
	s_nop 0
	global_load_lds_dwordx4 v65, s[58:59]
	s_add_u32 m0, s61, 0xa000
	s_nop 0
	global_load_lds_dwordx4 v66, s[58:59]
	s_add_u32 m0, s61, 0xb000
	s_nop 0
	global_load_lds_dwordx4 v67, s[58:59]
	s_add_u32 s56, s56, 0x80
	s_addc_u32 s57, s57, 0
	s_add_u32 s58, s58, 0x80
	s_addc_u32 s59, s59, 0
	s_add_u32 m0, s61, 0x4000
	s_nop 0
	global_load_lds_dwordx4 v64, s[56:57]
	s_add_u32 m0, s61, 0x5000
	s_nop 0
	global_load_lds_dwordx4 v65, s[56:57]
	s_add_u32 m0, s61, 0x6000
	s_nop 0
	global_load_lds_dwordx4 v66, s[56:57]
	s_add_u32 m0, s61, 0x7000
	s_nop 0
	global_load_lds_dwordx4 v67, s[56:57]
	s_add_u32 m0, s61, 0xc000
	s_nop 0
	global_load_lds_dwordx4 v64, s[58:59]
	s_add_u32 m0, s61, 0xd000
	s_nop 0
	global_load_lds_dwordx4 v65, s[58:59]
	s_add_u32 m0, s61, 0xe000
	s_nop 0
	global_load_lds_dwordx4 v66, s[58:59]
	s_add_u32 m0, s61, 0xf000
	s_nop 0
	global_load_lds_dwordx4 v67, s[58:59]
	s_add_u32 s56, s56, 0x80
	s_addc_u32 s57, s57, 0
	s_add_u32 s58, s58, 0x80
	s_addc_u32 s59, s59, 0
	s_waitcnt vmcnt(8)
	s_barrier
	ds_read_b128 v[186:189], v142 offset:0
	ds_read_b128 v[190:193], v142 offset:4096
	ds_read_b128 v[194:197], v143 offset:32768
	ds_read_b128 v[198:201], v143 offset:36864
	ds_read_b128 v[202:205], v144 offset:0
	ds_read_b128 v[206:209], v144 offset:4096
	ds_read_b128 v[210:213], v145 offset:32768
	ds_read_b128 v[214:217], v145 offset:36864
	ds_read_b128 v[218:221], v146 offset:0
	ds_read_b128 v[222:225], v146 offset:4096
	ds_read_b128 v[226:229], v147 offset:32768
	ds_read_b128 v[230:233], v147 offset:36864
	s_mov_b32 s60, 0
	ds_read_b128 v[234:237], v148 offset:0
	ds_read_b128 v[238:241], v148 offset:4096
	ds_read_b128 v[242:245], v149 offset:32768
	ds_read_b128 v[246:249], v149 offset:36864
	s_waitcnt lgkmcnt(12)
	v_mfma_f32_32x32x16_bf16 v[32:47], v[186:189], v[194:197], 0
	v_mfma_f32_32x32x16_bf16 v[48:63], v[186:189], v[198:201], 0
	v_mfma_f32_32x32x16_bf16 v[0:15], v[190:193], v[194:197], 0
	v_mfma_f32_32x32x16_bf16 v[16:31], v[190:193], v[198:201], 0
	s_waitcnt vmcnt(0) lgkmcnt(0)
	s_barrier
	s_branch .Lgm_body0_gemmF2

.Lgm_body0_gemmF2:
	ds_read_b128 v[186:189], v142 offset:16384
	s_add_u32 m0, s61, 0x0
	s_nop 0
	global_load_lds_dwordx4 v64, s[56:57]
	v_mfma_f32_32x32x16_bf16 v[32:47], v[202:205], v[210:213], v[32:47]
	ds_read_b128 v[190:193], v142 offset:20480
	s_add_u32 m0, s61, 0x1000
	s_nop 0
	global_load_lds_dwordx4 v65, s[56:57]
	v_mfma_f32_32x32x16_bf16 v[48:63], v[202:205], v[214:217], v[48:63]
	ds_read_b128 v[194:197], v143 offset:49152
	s_add_u32 m0, s61, 0x2000
	s_nop 0
	global_load_lds_dwordx4 v66, s[56:57]
	v_mfma_f32_32x32x16_bf16 v[0:15], v[206:209], v[210:213], v[0:15]
	ds_read_b128 v[198:201], v143 offset:53248
	s_add_u32 m0, s61, 0x3000
	s_nop 0
	global_load_lds_dwordx4 v67, s[56:57]
	v_mfma_f32_32x32x16_bf16 v[16:31], v[206:209], v[214:217], v[16:31]
	ds_read_b128 v[202:205], v144 offset:16384
	s_add_u32 m0, s61, 0x8000
	s_nop 0
	global_load_lds_dwordx4 v64, s[58:59]
	v_mfma_f32_32x32x16_bf16 v[32:47], v[218:221], v[226:229], v[32:47]
	ds_read_b128 v[206:209], v144 offset:20480
	s_add_u32 m0, s61, 0x9000
	s_nop 0
	global_load_lds_dwordx4 v65, s[58:59]
	v_mfma_f32_32x32x16_bf16 v[48:63], v[218:221], v[230:233], v[48:63]
	ds_read_b128 v[210:213], v145 offset:49152
	s_add_u32 m0, s61, 0xa000
	s_nop 0
	global_load_lds_dwordx4 v66, s[58:59]
	v_mfma_f32_32x32x16_bf16 v[0:15], v[222:225], v[226:229], v[0:15]
	ds_read_b128 v[214:217], v145 offset:53248
	s_add_u32 m0, s61, 0xb000
	s_nop 0
	global_load_lds_dwordx4 v67, s[58:59]
	v_mfma_f32_32x32x16_bf16 v[16:31], v[222:225], v[230:233], v[16:31]
	ds_read_b128 v[218:221], v146 offset:16384
	s_add_u32 s56, s56, 0x80
	s_addc_u32 s57, s57, 0
	s_add_u32 s58, s58, 0x80
	s_addc_u32 s59, s59, 0
	v_mfma_f32_32x32x16_bf16 v[32:47], v[234:237], v[242:245], v[32:47]
	ds_read_b128 v[222:225], v146 offset:20480
	v_mfma_f32_32x32x16_bf16 v[48:63], v[234:237], v[246:249], v[48:63]
	ds_read_b128 v[226:229], v147 offset:49152
	v_mfma_f32_32x32x16_bf16 v[0:15], v[238:241], v[242:245], v[0:15]
	ds_read_b128 v[230:233], v147 offset:53248
	v_mfma_f32_32x32x16_bf16 v[16:31], v[238:241], v[246:249], v[16:31]
	s_branch .Lgm_join0_gemmF2

.LBB0_1012:
	s_lshl_b32 s6, s29, 7
	s_and_b32 s30, s6, 0x1f80
	s_lshl_b32 s6, s30, 12
	s_ashr_i32 s12, s29, 6
	s_lshl_b32 s14, s12, 7
	s_ashr_i32 s15, s14, 31
	s_lshl_b32 s26, s14, 12
	s_add_u32 s16, s88, 0x3f80000
	s_addc_u32 s17, s89, 0
	s_add_u32 s16, s16, s6
	s_addc_u32 s17, s17, 0
	s_add_u32 s20, s88, 0x2e80000
	s_addc_u32 s21, s89, 0
	s_add_u32 s20, s20, s26
	s_addc_u32 s21, s21, 0
	v_readfirstlane_b32 s25, v168
	v_lshrrev_b32_e32 v190, 3, v168
	v_bfe_u32 v191, v168, 4, 3
	v_and_b32_e32 v192, 7, v168
	v_xor_b32_e32 v191, v191, v192
	v_lshlrev_b32_e32 v191, 4, v191
	s_lshr_b32 s25, s25, 6
	s_lshl_b32 s25, s25, 10
	s_movk_i32 s6, 0x1000
	v_mul_lo_u32 v190, v190, s6
	v_add_u32_e32 v190, v190, v191
	v_add_u32_e32 v191, 0x20000, v190
	v_add_u32_e32 v192, 0x40000, v190
	v_add_u32_e32 v193, 0x60000, v190
	v_add_u32_e32 v194, v129, v150
	v_add_u32_e32 v198, v137, v150
	v_add_u32_e32 v195, v129, v151
	v_add_u32_e32 v199, v137, v151
	v_add_u32_e32 v196, v129, v152
	v_add_u32_e32 v200, v137, v152
	v_add_u32_e32 v197, v129, v153
	v_add_u32_e32 v201, v137, v153
	s_add_u32 m0, s25, 0x0
	s_nop 0
	global_load_lds_dwordx4 v190, s[16:17]
	s_add_u32 m0, s25, 0x1000
	s_nop 0
	global_load_lds_dwordx4 v191, s[16:17]
	s_add_u32 m0, s25, 0x2000
	s_nop 0
	global_load_lds_dwordx4 v192, s[16:17]
	s_add_u32 m0, s25, 0x3000
	s_nop 0
	global_load_lds_dwordx4 v193, s[16:17]
	s_add_u32 m0, s25, 0x8000
	s_nop 0
	global_load_lds_dwordx4 v190, s[20:21]
	s_add_u32 m0, s25, 0x9000
	s_nop 0
	global_load_lds_dwordx4 v191, s[20:21]
	s_add_u32 m0, s25, 0xa000
	s_nop 0
	global_load_lds_dwordx4 v192, s[20:21]
	s_add_u32 m0, s25, 0xb000
	s_nop 0
	global_load_lds_dwordx4 v193, s[20:21]
	s_add_u32 s16, s16, 0x80
	s_addc_u32 s17, s17, 0
	s_add_u32 s20, s20, 0x80
	s_addc_u32 s21, s21, 0
	s_add_u32 m0, s25, 0x4000
	s_nop 0
	global_load_lds_dwordx4 v190, s[16:17]
	s_add_u32 m0, s25, 0x5000
	s_nop 0
	global_load_lds_dwordx4 v191, s[16:17]
	s_add_u32 m0, s25, 0x6000
	s_nop 0
	global_load_lds_dwordx4 v192, s[16:17]
	s_add_u32 m0, s25, 0x7000
	s_nop 0
	global_load_lds_dwordx4 v193, s[16:17]
	s_add_u32 m0, s25, 0xc000
	s_nop 0
	global_load_lds_dwordx4 v190, s[20:21]
	s_add_u32 m0, s25, 0xd000
	s_nop 0
	global_load_lds_dwordx4 v191, s[20:21]
	s_add_u32 m0, s25, 0xe000
	s_nop 0
	global_load_lds_dwordx4 v192, s[20:21]
	s_add_u32 m0, s25, 0xf000
	s_nop 0
	global_load_lds_dwordx4 v193, s[20:21]
	s_add_u32 s16, s16, 0x80
	s_addc_u32 s17, s17, 0
	s_add_u32 s20, s20, 0x80
	s_addc_u32 s21, s21, 0
	s_waitcnt vmcnt(8)
	s_barrier
	ds_read_b128 v[64:67], v194 offset:0
	ds_read_b128 v[68:71], v194 offset:4096
	ds_read_b128 v[72:75], v198 offset:32768
	ds_read_b128 v[76:79], v198 offset:36864
	ds_read_b128 v[80:83], v195 offset:0
	ds_read_b128 v[84:87], v195 offset:4096
	ds_read_b128 v[88:91], v199 offset:32768
	ds_read_b128 v[92:95], v199 offset:36864
	ds_read_b128 v[96:99], v196 offset:0
	ds_read_b128 v[100:103], v196 offset:4096
	ds_read_b128 v[104:107], v200 offset:32768
	ds_read_b128 v[108:111], v200 offset:36864
	s_mov_b32 s6, 0
	ds_read_b128 v[112:115], v197 offset:0
	ds_read_b128 v[116:119], v197 offset:4096
	ds_read_b128 v[120:123], v201 offset:32768
	ds_read_b128 v[124:127], v201 offset:36864
	s_waitcnt lgkmcnt(12)
	v_mfma_f32_32x32x16_bf16 v[48:63], v[64:67], v[72:75], 0
	v_mfma_f32_32x32x16_bf16 v[32:47], v[64:67], v[76:79], 0
	v_mfma_f32_32x32x16_bf16 v[16:31], v[68:71], v[72:75], 0
	v_mfma_f32_32x32x16_bf16 v[0:15], v[68:71], v[76:79], 0
	s_waitcnt vmcnt(0) lgkmcnt(0)
	s_barrier
	s_branch .Lgm_body0_G

.Lgm_body0_G:
	ds_read_b128 v[64:67], v194 offset:16384
	s_add_u32 m0, s25, 0x0
	s_nop 0
	global_load_lds_dwordx4 v190, s[16:17]
	v_mfma_f32_32x32x16_bf16 v[48:63], v[80:83], v[88:91], v[48:63]
	ds_read_b128 v[68:71], v194 offset:20480
	s_add_u32 m0, s25, 0x1000
	s_nop 0
	global_load_lds_dwordx4 v191, s[16:17]
	v_mfma_f32_32x32x16_bf16 v[32:47], v[80:83], v[92:95], v[32:47]
	ds_read_b128 v[72:75], v198 offset:49152
	s_add_u32 m0, s25, 0x2000
	s_nop 0
	global_load_lds_dwordx4 v192, s[16:17]
	v_mfma_f32_32x32x16_bf16 v[16:31], v[84:87], v[88:91], v[16:31]
	ds_read_b128 v[76:79], v198 offset:53248
	s_add_u32 m0, s25, 0x3000
	s_nop 0
	global_load_lds_dwordx4 v193, s[16:17]
	v_mfma_f32_32x32x16_bf16 v[0:15], v[84:87], v[92:95], v[0:15]
	ds_read_b128 v[80:83], v195 offset:16384
	s_add_u32 m0, s25, 0x8000
	s_nop 0
	global_load_lds_dwordx4 v190, s[20:21]
	v_mfma_f32_32x32x16_bf16 v[48:63], v[96:99], v[104:107], v[48:63]
	ds_read_b128 v[84:87], v195 offset:20480
	s_add_u32 m0, s25, 0x9000
	s_nop 0
	global_load_lds_dwordx4 v191, s[20:21]
	v_mfma_f32_32x32x16_bf16 v[32:47], v[96:99], v[108:111], v[32:47]
	ds_read_b128 v[88:91], v199 offset:49152
	s_add_u32 m0, s25, 0xa000
	s_nop 0
	global_load_lds_dwordx4 v192, s[20:21]
	v_mfma_f32_32x32x16_bf16 v[16:31], v[100:103], v[104:107], v[16:31]
	ds_read_b128 v[92:95], v199 offset:53248
	s_add_u32 m0, s25, 0xb000
	s_nop 0
	global_load_lds_dwordx4 v193, s[20:21]
	v_mfma_f32_32x32x16_bf16 v[0:15], v[100:103], v[108:111], v[0:15]
	ds_read_b128 v[96:99], v196 offset:16384
	s_add_u32 s16, s16, 0x80
	s_addc_u32 s17, s17, 0
	s_add_u32 s20, s20, 0x80
	s_addc_u32 s21, s21, 0
	v_mfma_f32_32x32x16_bf16 v[48:63], v[112:115], v[120:123], v[48:63]
	ds_read_b128 v[100:103], v196 offset:20480
	v_mfma_f32_32x32x16_bf16 v[32:47], v[112:115], v[124:127], v[32:47]
	ds_read_b128 v[104:107], v200 offset:49152
	v_mfma_f32_32x32x16_bf16 v[16:31], v[116:119], v[120:123], v[16:31]
	ds_read_b128 v[108:111], v200 offset:53248
	v_mfma_f32_32x32x16_bf16 v[0:15], v[116:119], v[124:127], v[0:15]
	s_branch .Lgm_join0_G

.LBB0_1102:
	s_or_b64 exec, exec, s[0:1]
	s_lshl_b32 s0, s38, 12
	s_lshl_b32 s12, s2, 12
	s_waitcnt lgkmcnt(0)
	s_add_u32 s16, s88, 0x5f80000
	s_addc_u32 s17, s89, 0
	s_add_u32 s16, s16, s0
	s_addc_u32 s17, s17, 0
	s_add_u32 s34, s88, 0x3680000
	s_addc_u32 s35, s89, 0
	s_add_u32 s34, s34, s12
	s_addc_u32 s35, s35, 0
	v_readfirstlane_b32 s36, v168
	v_lshrrev_b32_e32 v188, 3, v168
	v_bfe_u32 v189, v168, 4, 3
	v_and_b32_e32 v190, 7, v168
	v_xor_b32_e32 v189, v189, v190
	v_lshlrev_b32_e32 v189, 4, v189
	s_lshr_b32 s36, s36, 6
	s_lshl_b32 s36, s36, 10
	s_movk_i32 s12, 0x1000
	v_mul_lo_u32 v188, v188, s12
	v_add_u32_e32 v188, v188, v189
	v_add_u32_e32 v189, 0x20000, v188
	v_add_u32_e32 v190, 0x40000, v188
	v_add_u32_e32 v191, 0x60000, v188
	s_add_u32 m0, s36, 0x0
	s_nop 0
	global_load_lds_dwordx4 v188, s[16:17]
	s_add_u32 m0, s36, 0x1000
	s_nop 0
	global_load_lds_dwordx4 v189, s[16:17]
	s_add_u32 m0, s36, 0x2000
	s_nop 0
	global_load_lds_dwordx4 v190, s[16:17]
	s_add_u32 m0, s36, 0x3000
	s_nop 0
	global_load_lds_dwordx4 v191, s[16:17]
	s_add_u32 m0, s36, 0x8000
	s_nop 0
	global_load_lds_dwordx4 v188, s[34:35]
	s_add_u32 m0, s36, 0x9000
	s_nop 0
	global_load_lds_dwordx4 v189, s[34:35]
	s_add_u32 m0, s36, 0xa000
	s_nop 0
	global_load_lds_dwordx4 v190, s[34:35]
	s_add_u32 m0, s36, 0xb000
	s_nop 0
	global_load_lds_dwordx4 v191, s[34:35]
	s_add_u32 s16, s16, 0x80
	s_addc_u32 s17, s17, 0
	s_add_u32 s34, s34, 0x80
	s_addc_u32 s35, s35, 0
	s_add_u32 m0, s36, 0x4000
	s_nop 0
	global_load_lds_dwordx4 v188, s[16:17]
	s_add_u32 m0, s36, 0x5000
	s_nop 0
	global_load_lds_dwordx4 v189, s[16:17]
	s_add_u32 m0, s36, 0x6000
	s_nop 0
	global_load_lds_dwordx4 v190, s[16:17]
	s_add_u32 m0, s36, 0x7000
	s_nop 0
	global_load_lds_dwordx4 v191, s[16:17]
	s_add_u32 m0, s36, 0xc000
	s_nop 0
	global_load_lds_dwordx4 v188, s[34:35]
	s_add_u32 m0, s36, 0xd000
	s_nop 0
	global_load_lds_dwordx4 v189, s[34:35]
	s_add_u32 m0, s36, 0xe000
	s_nop 0
	global_load_lds_dwordx4 v190, s[34:35]
	s_add_u32 m0, s36, 0xf000
	s_nop 0
	global_load_lds_dwordx4 v191, s[34:35]
	s_add_u32 s16, s16, 0x80
	s_addc_u32 s17, s17, 0
	s_add_u32 s34, s34, 0x80
	s_addc_u32 s35, s35, 0
	s_waitcnt vmcnt(8)
	s_barrier
	ds_read_b128 v[64:67], v177 offset:0
	ds_read_b128 v[68:71], v177 offset:4096
	ds_read_b128 v[72:75], v178 offset:32768
	ds_read_b128 v[76:79], v178 offset:36864
	ds_read_b128 v[80:83], v179 offset:0
	ds_read_b128 v[84:87], v179 offset:4096
	ds_read_b128 v[88:91], v182 offset:32768
	ds_read_b128 v[92:95], v182 offset:36864
	ds_read_b128 v[96:99], v183 offset:0
	ds_read_b128 v[100:103], v183 offset:4096
	ds_read_b128 v[104:107], v184 offset:32768
	ds_read_b128 v[108:111], v184 offset:36864
	s_mov_b32 s12, 0
	ds_read_b128 v[112:115], v185 offset:0
	ds_read_b128 v[116:119], v185 offset:4096
	ds_read_b128 v[120:123], v186 offset:32768
	ds_read_b128 v[124:127], v186 offset:36864
	s_waitcnt lgkmcnt(12)
	v_mfma_f32_32x32x16_bf16 v[48:63], v[64:67], v[72:75], 0
	v_mfma_f32_32x32x16_bf16 v[32:47], v[64:67], v[76:79], 0
	v_mfma_f32_32x32x16_bf16 v[16:31], v[68:71], v[72:75], 0
	v_mfma_f32_32x32x16_bf16 v[0:15], v[68:71], v[76:79], 0
	s_waitcnt vmcnt(0) lgkmcnt(0)
	s_barrier
	s_branch .Lgm_body0_H

.Lgm_body0_H:
	ds_read_b128 v[64:67], v177 offset:16384
	s_add_u32 m0, s36, 0x0
	s_nop 0
	global_load_lds_dwordx4 v188, s[16:17]
	v_mfma_f32_32x32x16_bf16 v[48:63], v[80:83], v[88:91], v[48:63]
	ds_read_b128 v[68:71], v177 offset:20480
	s_add_u32 m0, s36, 0x1000
	s_nop 0
	global_load_lds_dwordx4 v189, s[16:17]
	v_mfma_f32_32x32x16_bf16 v[32:47], v[80:83], v[92:95], v[32:47]
	ds_read_b128 v[72:75], v178 offset:49152
	s_add_u32 m0, s36, 0x2000
	s_nop 0
	global_load_lds_dwordx4 v190, s[16:17]
	v_mfma_f32_32x32x16_bf16 v[16:31], v[84:87], v[88:91], v[16:31]
	ds_read_b128 v[76:79], v178 offset:53248
	s_add_u32 m0, s36, 0x3000
	s_nop 0
	global_load_lds_dwordx4 v191, s[16:17]
	v_mfma_f32_32x32x16_bf16 v[0:15], v[84:87], v[92:95], v[0:15]
	ds_read_b128 v[80:83], v179 offset:16384
	s_add_u32 m0, s36, 0x8000
	s_nop 0
	global_load_lds_dwordx4 v188, s[34:35]
	v_mfma_f32_32x32x16_bf16 v[48:63], v[96:99], v[104:107], v[48:63]
	ds_read_b128 v[84:87], v179 offset:20480
	s_add_u32 m0, s36, 0x9000
	s_nop 0
	global_load_lds_dwordx4 v189, s[34:35]
	v_mfma_f32_32x32x16_bf16 v[32:47], v[96:99], v[108:111], v[32:47]
	ds_read_b128 v[88:91], v182 offset:49152
	s_add_u32 m0, s36, 0xa000
	s_nop 0
	global_load_lds_dwordx4 v190, s[34:35]
	v_mfma_f32_32x32x16_bf16 v[16:31], v[100:103], v[104:107], v[16:31]
	ds_read_b128 v[92:95], v182 offset:53248
	s_add_u32 m0, s36, 0xb000
	s_nop 0
	global_load_lds_dwordx4 v191, s[34:35]
	v_mfma_f32_32x32x16_bf16 v[0:15], v[100:103], v[108:111], v[0:15]
	ds_read_b128 v[96:99], v183 offset:16384
	s_add_u32 s16, s16, 0x80
	s_addc_u32 s17, s17, 0
	s_add_u32 s34, s34, 0x80
	s_addc_u32 s35, s35, 0
	v_mfma_f32_32x32x16_bf16 v[48:63], v[112:115], v[120:123], v[48:63]
	ds_read_b128 v[100:103], v183 offset:20480
	v_mfma_f32_32x32x16_bf16 v[32:47], v[112:115], v[124:127], v[32:47]
	ds_read_b128 v[104:107], v184 offset:49152
	v_mfma_f32_32x32x16_bf16 v[16:31], v[116:119], v[120:123], v[16:31]
	ds_read_b128 v[108:111], v184 offset:53248
	v_mfma_f32_32x32x16_bf16 v[0:15], v[116:119], v[124:127], v[0:15]
	s_branch .Lgm_join0_H
